# attention DQK=128: K fragments of the QK MFMAs double-buffered in two register sets
# baseline (speedup 1.0000x reference)
; #define SBAR() __builtin_amdgcn_sched_barrier(0)
; __device__ __forceinline__ void partialSM2(f32x16& p0, f32x16& p1, float& m_hat, f32x16& negm, float& alpha) {
;     float pmax = fmaxf(p0[0], p0[1]);
; #pragma unroll
;     for (int r = 2; r < 16; ++r) pmax = fmaxf(pmax, p0[r]);
; #pragma unroll
;     for (int r = 0; r < 16; ++r) pmax = fmaxf(pmax, p1[r]);
;     { auto rr = __builtin_amdgcn_permlane32_swap(__float_as_uint(pmax), __float_as_uint(pmax), false, false);
;       pmax = fmaxf(__uint_as_float(rr[0]), __uint_as_float(rr[1])); }
;     if (__builtin_expect(__all(pmax <= THR2), 1)) { alpha = 1.f; }
; template <int DQK> __device__ __forceinline__ void qkt(f32x16& p0, f32x16& p1, const char* Ks, const bf16x8* qr, const char* qrl, int r32, int hi, const f32x16& c0) {
;     constexpr int ROWB = Cfg<DQK>::ROWB;
;     p0 = c0; p1 = c0;
; #pragma unroll
;     for (int d0 = 0; d0 < 8; ++d0) { const int cb = (d0 * 16 + hi * 8) * 2;
;         bf16x8 b0 = *reinterpret_cast<const bf16x8*>(Ks + r32 * ROWB + (cb ^ kswz<DQK>(r32)));
;         bf16x8 b1 = *reinterpret_cast<const bf16x8*>(Ks + (32 + r32) * ROWB + (cb ^ kswz<DQK>(r32)));
;         p0 = __builtin_amdgcn_mfma_f32_32x32x16_bf16(b0, qr[d0], p0, 0, 0, 0);
;         p1 = __builtin_amdgcn_mfma_f32_32x32x16_bf16(b1, qr[d0], p1, 0, 0, 0);
;         if constexpr (DQK == 192) { if (d0 == 3 || d0 == 7) SBAR(); } }
.LBB0_118:
	s_mov_b32 s16, s5
	s_mov_b32 s5, s15
	s_and_b32 s15, s7, 0x4000
	v_add_u32_e32 v0, s15, v213
	v_add_u32_e32 v246, v0, v214
	v_add_u32_e32 v247, v0, v215
	ds_read_b128 v[2:5], v246 offset:49152
	ds_read_b128 v[6:9], v246 offset:57344
	ds_read_b128 v[238:241], v247 offset:49152
	ds_read_b128 v[242:245], v247 offset:57344
	v_add_u32_e32 v246, v0, v229
	v_add_u32_e32 v247, v0, v230
	s_mov_b32 s20, 0x41000000
	s_waitcnt vmcnt(11) lgkmcnt(3)
	v_mfma_f32_32x32x16_bf16 v[128:143], v[2:5], v[144:147], v[96:111]
	s_waitcnt lgkmcnt(2)
	v_mfma_f32_32x32x16_bf16 v[112:127], v[6:9], v[144:147], v[96:111]
	ds_read_b128 v[2:5], v246 offset:49152
	ds_read_b128 v[6:9], v246 offset:57344
	v_add_u32_e32 v246, v0, v231
	s_waitcnt vmcnt(10) lgkmcnt(3)
	v_mfma_f32_32x32x16_bf16 v[128:143], v[238:241], v[148:151], v[128:143]
	s_waitcnt lgkmcnt(2)
	v_mfma_f32_32x32x16_bf16 v[112:127], v[242:245], v[148:151], v[112:127]
	ds_read_b128 v[238:241], v247 offset:49152
	ds_read_b128 v[242:245], v247 offset:57344
	v_add_u32_e32 v247, v0, v232
	s_waitcnt vmcnt(9) lgkmcnt(3)
	v_mfma_f32_32x32x16_bf16 v[128:143], v[2:5], v[152:155], v[128:143]
	s_waitcnt lgkmcnt(2)
	v_mfma_f32_32x32x16_bf16 v[112:127], v[6:9], v[152:155], v[112:127]
	ds_read_b128 v[2:5], v246 offset:49152
	ds_read_b128 v[6:9], v246 offset:57344
	v_add_u32_e32 v246, v0, v233
	s_waitcnt vmcnt(8) lgkmcnt(3)
	v_mfma_f32_32x32x16_bf16 v[128:143], v[238:241], v[156:159], v[128:143]
	s_waitcnt lgkmcnt(2)
	v_mfma_f32_32x32x16_bf16 v[112:127], v[242:245], v[156:159], v[112:127]
	ds_read_b128 v[238:241], v247 offset:49152
	ds_read_b128 v[242:245], v247 offset:57344
	v_add_u32_e32 v247, v0, v234
	s_waitcnt vmcnt(7) lgkmcnt(3)
	v_mfma_f32_32x32x16_bf16 v[128:143], v[2:5], v[160:163], v[128:143]
	s_waitcnt lgkmcnt(2)
	v_mfma_f32_32x32x16_bf16 v[112:127], v[6:9], v[160:163], v[112:127]
	ds_read_b128 v[2:5], v246 offset:49152
	ds_read_b128 v[6:9], v246 offset:57344
	s_waitcnt vmcnt(6) lgkmcnt(3)
	v_mfma_f32_32x32x16_bf16 v[128:143], v[238:241], v[164:167], v[128:143]
	s_waitcnt lgkmcnt(2)
	v_mfma_f32_32x32x16_bf16 v[112:127], v[242:245], v[164:167], v[112:127]
	ds_read_b128 v[238:241], v247 offset:49152
	ds_read_b128 v[242:245], v247 offset:57344
	s_waitcnt vmcnt(5) lgkmcnt(3)
	v_mfma_f32_32x32x16_bf16 v[128:143], v[2:5], v[168:171], v[128:143]
	s_waitcnt lgkmcnt(2)
	v_mfma_f32_32x32x16_bf16 v[112:127], v[6:9], v[168:171], v[112:127]
	s_waitcnt vmcnt(4) lgkmcnt(1)
	v_mfma_f32_32x32x16_bf16 v[128:143], v[238:241], v[172:175], v[128:143]
	s_waitcnt lgkmcnt(0)
	v_mfma_f32_32x32x16_bf16 v[112:127], v[242:245], v[172:175], v[112:127]
	s_nop 9
	v_max_f32_e32 v0, v129, v129
	v_max_f32_e32 v2, v128, v128
	v_max_f32_e32 v0, v2, v0
	v_max3_f32 v0, v0, v130, v131
	v_max3_f32 v0, v0, v132, v133
	v_max3_f32 v0, v0, v134, v135
	v_max3_f32 v0, v0, v136, v137
	v_max3_f32 v0, v0, v138, v139
	v_max3_f32 v0, v0, v140, v141
	v_max3_f32 v0, v0, v142, v143
	v_max3_f32 v0, v0, v112, v113
	v_max3_f32 v0, v0, v114, v115
	v_max3_f32 v0, v0, v116, v117
	v_max3_f32 v0, v0, v118, v119
	v_max3_f32 v0, v0, v120, v121
	v_max3_f32 v0, v0, v122, v123
	v_max3_f32 v0, v0, v124, v125
	v_max3_f32 v0, v0, v126, v127
	v_mov_b32_e32 v2, v0
	s_nop 1
	v_permlane32_swap_b32_e32 v0, v2
	v_max_f32_e32 v2, v2, v2
	v_max_f32_e32 v0, v0, v0
	v_max_f32_e32 v2, v0, v2
	v_cmp_ge_f32_e32 vcc, s20, v2
	s_cmp_eq_u64 vcc, exec
	v_mov_b32_e32 v0, 1.0
	s_cbranch_scc0 .LBB0_129
